# attention loop layout: non-diagonal PV fast path is the fall-through, diagonal (masked) path moved out of line; removes two taken branches per tile
# speedup vs baseline: 1.0060x; 1.0060x over previous
; __device__ __forceinline__ void finishSM(f32x16& p0, f32x16& p1, float alpha, float& l_reg, bf16x8& pa0, bf16x8& pa1, bf16x8& pa2, bf16x8& pa3) {
; #pragma unroll
;     for (int r = 0; r < 16; ++r) p1[r] = __builtin_amdgcn_exp2f(p1[r]);
;     float ps = 0;
; #pragma unroll
;     for (int r = 0; r < 16; ++r) ps += p0[r];
; #pragma unroll
;     for (int r = 0; r < 16; ++r) ps += p1[r];
;     { auto rr = __builtin_amdgcn_permlane32_swap(__float_as_uint(ps), __float_as_uint(ps), false, false);
;       ps = __uint_as_float(rr[0]) + __uint_as_float(rr[1]); }
;     l_reg = l_reg * alpha + ps;
;     ...
;     PK4(p0, 0, pa0); PK4(p0, 8, pa1); PK4(p1, 0, pa2); PK4(p1, 8, pa3);
;     ...
; }
; template <int KB>
; __device__ __forceinline__ void qkt(f32x16& p0, f32x16& p1, const char* K_lds, int r32, int hi, const bf16x8* qr, const char* qbase) {
;     p0 = f32x16{}; p1 = f32x16{};
;     const char* kbp = K_lds + KB * SHM_K + r32 * KROW + hi * 16;
; #pragma unroll
;     for (int d0 = 0; d0 < 12; ++d0) { const char* a = kbp + d0 * 32;
;         bf16x8 b0 = *reinterpret_cast<const bf16x8*>(a);
;         bf16x8 b1 = *reinterpret_cast<const bf16x8*>(a + 32 * KROW);
;         const bf16x8 qf = d0 < 4 ? qr[d0 & 3] : *reinterpret_cast<const bf16x8*>(qbase + (d0 - 4) * 32);
;         p0 = __builtin_amdgcn_mfma_f32_32x32x16_bf16(b0, qf, p0, 0, 0, 0);
;         p1 = __builtin_amdgcn_mfma_f32_32x32x16_bf16(b1, qf, p1, 0, 0, 0); }
; }
.LBB0_1481:
	ds_read_b128 v[64:67], v202 offset:58368
	s_waitcnt vmcnt(0)
	ds_read_b128 v[100:103], v202 offset:58400
	v_add_u32_e32 v254, s31, v183
	v_add_u32_e32 v250, 0x80, v254
	v_min_u32_e32 v252, 0x100f, v250
	v_add_u32_e32 v251, 0x4080, v254
	v_add_u32_e32 v252, s14, v252
	v_cmp_gt_i32_e32 vcc, 16, v250
	s_nop 1
	v_cndmask_b32_e32 v250, v252, v251, vcc
	v_ashrrev_i32_e32 v251, 31, v250
	v_mad_i64_i32 v[252:253], s[0:1], v250, s33, v[184:185]
	v_lshlrev_b64 v[250:251], 12, v[250:251]
	v_lshl_add_u64 v[250:251], v[186:187], 0, v[250:251]
	global_load_dwordx4 v[146:149], v[250:251], off offset:128
	global_load_dwordx4 v[150:153], v[252:253], off
	global_load_dwordx4 v[154:157], v[252:253], off offset:128
	global_load_dwordx4 v[162:165], v[250:251], off
	global_load_dwordx4 v[158:161], v[252:253], off offset:256
	v_exp_f32_e32 v112, v172
	v_exp_f32_e32 v113, v173
	v_exp_f32_e32 v114, v170
	s_waitcnt lgkmcnt(1)
	v_mfma_f32_32x32x16_bf16 v[84:99], v[64:67], v[142:145], 0
	ds_read_b128 v[64:67], v206 offset:12800
	ds_read_b128 v[104:107], v206 offset:12832
	v_exp_f32_e32 v115, v171
	v_exp_f32_e32 v116, v168
	v_exp_f32_e32 v117, v169
	v_exp_f32_e32 v118, v166
	v_exp_f32_e32 v119, v167
	s_waitcnt lgkmcnt(1)
	v_mfma_f32_32x32x16_bf16 v[68:83], v[64:67], v[142:145], 0
	v_mfma_f32_32x32x16_bf16 v[84:99], v[100:103], v[138:141], v[84:99]
	ds_read_b128 v[64:67], v202 offset:58432
	ds_read_b128 v[100:103], v206 offset:12864
	v_add_f32_e32 v255, 0, v233
	v_add_f32_e32 v255, v235, v255
	s_waitcnt lgkmcnt(2)
	v_mfma_f32_32x32x16_bf16 v[68:83], v[104:107], v[138:141], v[68:83]
	v_add_f32_e32 v255, v231, v255
	v_add_f32_e32 v255, v234, v255
	s_waitcnt lgkmcnt(1)
	v_mfma_f32_32x32x16_bf16 v[84:99], v[64:67], v[134:137], v[84:99]
	v_add_f32_e32 v255, v223, v255
	v_add_f32_e32 v255, v232, v255
	s_waitcnt lgkmcnt(0)
	v_mfma_f32_32x32x16_bf16 v[68:83], v[100:103], v[134:137], v[68:83]
	ds_read_b128 v[64:67], v202 offset:58464
	ds_read_b128 v[100:103], v206 offset:12896
	v_add_f32_e32 v255, v221, v255
	v_add_f32_e32 v255, v222, v255
	s_waitcnt lgkmcnt(1)
	v_mfma_f32_32x32x16_bf16 v[84:99], v[64:67], v[130:133], v[84:99]
	v_add_f32_e32 v255, v217, v255
	v_add_f32_e32 v255, v220, v255
	s_waitcnt lgkmcnt(0)
	v_mfma_f32_32x32x16_bf16 v[68:83], v[100:103], v[130:133], v[68:83]
	ds_read_b128 v[64:67], v202 offset:58496
	ds_read_b128 v[100:103], v206 offset:12928
	ds_read_b128 v[104:107], v201
	ds_read_b128 v[108:111], v201 offset:32
	v_add_f32_e32 v255, v215, v255
	v_add_f32_e32 v255, v218, v255
	s_waitcnt lgkmcnt(1)
	v_mfma_f32_32x32x16_bf16 v[84:99], v[64:67], v[104:107], v[84:99]
	v_mfma_f32_32x32x16_bf16 v[68:83], v[100:103], v[104:107], v[68:83]
	ds_read_b128 v[64:67], v202 offset:58528
	ds_read_b128 v[100:103], v206 offset:12960
	v_add_f32_e32 v255, v213, v255
	v_add_f32_e32 v255, v219, v255
	s_waitcnt lgkmcnt(1)
	v_mfma_f32_32x32x16_bf16 v[84:99], v[64:67], v[108:111], v[84:99]
	v_add_f32_e32 v255, v214, v255
	v_add_f32_e32 v255, v216, v255
	s_waitcnt lgkmcnt(0)
	v_mfma_f32_32x32x16_bf16 v[68:83], v[100:103], v[108:111], v[68:83]
	ds_read_b128 v[64:67], v202 offset:58560
	ds_read_b128 v[100:103], v206 offset:12992
	ds_read_b128 v[104:107], v201 offset:64
	v_exp_f32_e32 v108, v176
	v_exp_f32_e32 v109, v177
	v_exp_f32_e32 v110, v174
	v_exp_f32_e32 v111, v175
	v_add_f32_e32 v255, v112, v255
	v_add_f32_e32 v255, v113, v255
	s_waitcnt lgkmcnt(0)
	v_mfma_f32_32x32x16_bf16 v[84:99], v[64:67], v[104:107], v[84:99]
	v_mfma_f32_32x32x16_bf16 v[68:83], v[100:103], v[104:107], v[68:83]
	ds_read_b128 v[64:67], v202 offset:58592
	ds_read_b128 v[100:103], v206 offset:13024
	ds_read_b128 v[104:107], v201 offset:96
	v_add_f32_e32 v255, v114, v255
	v_add_f32_e32 v255, v115, v255
	s_waitcnt lgkmcnt(0)
	v_mfma_f32_32x32x16_bf16 v[84:99], v[64:67], v[104:107], v[84:99]
	v_mfma_f32_32x32x16_bf16 v[68:83], v[100:103], v[104:107], v[68:83]
	ds_read_b128 v[64:67], v202 offset:58624
	ds_read_b128 v[100:103], v206 offset:13056
	ds_read_b128 v[104:107], v201 offset:128
	v_add_f32_e32 v255, v116, v255
	v_add_f32_e32 v255, v117, v255
	s_waitcnt lgkmcnt(0)
	v_mfma_f32_32x32x16_bf16 v[84:99], v[64:67], v[104:107], v[84:99]
	v_mfma_f32_32x32x16_bf16 v[68:83], v[100:103], v[104:107], v[68:83]
	ds_read_b128 v[64:67], v202 offset:58656
	ds_read_b128 v[100:103], v206 offset:13088
	ds_read_b128 v[104:107], v201 offset:160
	v_add_f32_e32 v255, v118, v255
	v_add_f32_e32 v255, v119, v255
	s_waitcnt lgkmcnt(0)
	v_mfma_f32_32x32x16_bf16 v[84:99], v[64:67], v[104:107], v[84:99]
	v_mfma_f32_32x32x16_bf16 v[68:83], v[100:103], v[104:107], v[68:83]
	ds_read_b128 v[64:67], v202 offset:58688
	ds_read_b128 v[100:103], v206 offset:13120
	ds_read_b128 v[104:107], v201 offset:192
	v_add_f32_e32 v255, v108, v255
	v_add_f32_e32 v255, v109, v255
	s_waitcnt lgkmcnt(0)
	v_mfma_f32_32x32x16_bf16 v[84:99], v[64:67], v[104:107], v[84:99]
	v_mfma_f32_32x32x16_bf16 v[68:83], v[100:103], v[104:107], v[68:83]
	ds_read_b128 v[64:67], v202 offset:58720
	ds_read_b128 v[100:103], v206 offset:13152
	ds_read_b128 v[104:107], v201 offset:224
	v_add_f32_e32 v255, v110, v255
	v_add_f32_e32 v255, v111, v255
	s_waitcnt lgkmcnt(0)
	v_mfma_f32_32x32x16_bf16 v[84:99], v[64:67], v[104:107], v[84:99]
	v_mfma_f32_32x32x16_bf16 v[68:83], v[100:103], v[104:107], v[68:83]
	v_exp_f32_e32 v104, v180
	v_exp_f32_e32 v105, v181
	v_exp_f32_e32 v106, v178
	v_exp_f32_e32 v107, v179
	v_add_f32_e32 v255, v104, v255
	v_add_f32_e32 v255, v105, v255
	v_add_f32_e32 v255, v106, v255
	v_add_f32_e32 v210, v107, v255
	v_mov_b32_e32 v211, v210
	s_nop 1
	v_permlane32_swap_b32_e32 v210, v211
	v_cvt_pk_bf16_f32 v64, v233, v235
	v_cvt_pk_bf16_f32 v65, v231, v234
	v_cvt_pk_bf16_f32 v66, v223, v232
	v_cvt_pk_bf16_f32 v67, v221, v222
	v_cvt_pk_bf16_f32 v100, v217, v220
	v_cvt_pk_bf16_f32 v101, v215, v218
	v_cvt_pk_bf16_f32 v102, v213, v219
	v_cvt_pk_bf16_f32 v103, v214, v216
	v_cvt_pk_bf16_f32 v104, v104, v105
	v_cvt_pk_bf16_f32 v105, v106, v107
	v_cvt_pk_bf16_f32 v106, v108, v109
	v_cvt_pk_bf16_f32 v107, v110, v111
	v_cvt_pk_bf16_f32 v108, v112, v113
	v_cvt_pk_bf16_f32 v109, v114, v115
	v_cvt_pk_bf16_f32 v110, v116, v117
	v_cvt_pk_bf16_f32 v111, v118, v119
	s_nop 0
	v_permlane32_swap_b32_e32 v64, v66
	v_permlane32_swap_b32_e32 v65, v67
	v_permlane32_swap_b32_e32 v100, v102
	v_permlane32_swap_b32_e32 v101, v103
	v_permlane32_swap_b32_e32 v104, v106
	v_permlane32_swap_b32_e32 v105, v107
	v_permlane32_swap_b32_e32 v108, v110
	v_permlane32_swap_b32_e32 v109, v111
	s_add_i32 s0, s31, 0x7f
	s_cmp_le_i32 s0, s30
	s_cbranch_scc0 .La_diag1
; __device__ __forceinline__ void partialSM(f32x16& p0, f32x16& p1, float& m_reg, float& mn, float& alpha) {
;     float pmax = p0[0];
; #pragma unroll
;     for (int r = 1; r < 16; ++r) pmax = fmaxf(pmax, p0[r]);
; #pragma unroll
;     for (int r = 0; r < 16; ++r) pmax = fmaxf(pmax, p1[r]);
;     { auto rr = __builtin_amdgcn_permlane32_swap(__float_as_uint(pmax), __float_as_uint(pmax), false, false);
;       pmax = fmaxf(__uint_as_float(rr[0]), __uint_as_float(rr[1])); }
;     constexpr float C2 = 1.4426950408889634f * SCALE;
;     if (__builtin_expect(__all((pmax - m_reg) * SCALE <= THR), 1)) { mn = m_reg; alpha = 1.f; }
;     else { mn = fmaxf(m_reg, pmax); alpha = __builtin_amdgcn_exp2f((m_reg - mn) * C2); m_reg = mn; }
; template <int VB>
; __device__ __forceinline__ void pv_tile(f32x16* o, int vb0, bf16x8 pa0, bf16x8 pa1, bf16x8 pa2, bf16x8 pa3) {
;     ...
;     PV_D0(0); PV_D0(1); PV_D0(2); PV_D0(3);
	ds_read_b64_tr_b16 v[112:113], v199 offset:0
	ds_read_b64_tr_b16 v[114:115], v199 offset:0x800
	ds_read_b64_tr_b16 v[116:117], v199 offset:0x1000
	ds_read_b64_tr_b16 v[118:119], v199 offset:0x1800
	ds_read_b64_tr_b16 v[120:121], v199 offset:0x2000
	ds_read_b64_tr_b16 v[122:123], v199 offset:0x2800
	ds_read_b64_tr_b16 v[124:125], v199 offset:0x3000
	ds_read_b64_tr_b16 v[126:127], v199 offset:0x3800
	s_waitcnt lgkmcnt(0)
	s_nop 0
	v_mfma_f32_32x32x16_bf16 v[48:63], v[64:67], v[112:115], v[48:63]
	v_max_f32_e32 v250, v85, v85
	v_max_f32_e32 v251, v84, v84
	ds_read_b64_tr_b16 v[112:113], v199 offset:0x200
	ds_read_b64_tr_b16 v[114:115], v199 offset:0xa00
	v_mfma_f32_32x32x16_bf16 v[48:63], v[100:103], v[116:119], v[48:63]
	v_max_f32_e32 v250, v251, v250
	v_max3_f32 v250, v250, v86, v87
	ds_read_b64_tr_b16 v[116:117], v199 offset:0x1200
	ds_read_b64_tr_b16 v[118:119], v199 offset:0x1a00
	v_mfma_f32_32x32x16_bf16 v[48:63], v[104:107], v[120:123], v[48:63]
	v_max3_f32 v250, v250, v88, v89
	v_max3_f32 v250, v250, v90, v91
	ds_read_b64_tr_b16 v[120:121], v199 offset:0x2200
	ds_read_b64_tr_b16 v[122:123], v199 offset:0x2a00
	v_mfma_f32_32x32x16_bf16 v[48:63], v[108:111], v[124:127], v[48:63]
	v_max3_f32 v250, v250, v92, v93
	v_max3_f32 v250, v250, v94, v95
	ds_read_b64_tr_b16 v[124:125], v199 offset:0x3200
	ds_read_b64_tr_b16 v[126:127], v199 offset:0x3a00
	s_waitcnt lgkmcnt(0)
	v_mfma_f32_32x32x16_bf16 v[32:47], v[64:67], v[112:115], v[32:47]
	v_max3_f32 v250, v250, v96, v97
	v_max3_f32 v250, v250, v98, v99
	ds_read_b64_tr_b16 v[112:113], v199 offset:0x400
	ds_read_b64_tr_b16 v[114:115], v199 offset:0xc00
	v_mfma_f32_32x32x16_bf16 v[32:47], v[100:103], v[116:119], v[32:47]
	v_max3_f32 v250, v250, v68, v69
	v_max3_f32 v250, v250, v70, v71
	ds_read_b64_tr_b16 v[116:117], v199 offset:0x1400
	ds_read_b64_tr_b16 v[118:119], v199 offset:0x1c00
	v_mfma_f32_32x32x16_bf16 v[32:47], v[104:107], v[120:123], v[32:47]
	v_max3_f32 v250, v250, v72, v73
	v_max3_f32 v250, v250, v74, v75
	ds_read_b64_tr_b16 v[120:121], v199 offset:0x2400
	ds_read_b64_tr_b16 v[122:123], v199 offset:0x2c00
	v_mfma_f32_32x32x16_bf16 v[32:47], v[108:111], v[124:127], v[32:47]
	v_max3_f32 v250, v250, v76, v77
	v_max3_f32 v250, v250, v78, v79
	ds_read_b64_tr_b16 v[124:125], v199 offset:0x3400
	ds_read_b64_tr_b16 v[126:127], v199 offset:0x3c00
	s_waitcnt lgkmcnt(0)
	v_mfma_f32_32x32x16_bf16 v[16:31], v[64:67], v[112:115], v[16:31]
	v_max3_f32 v250, v250, v80, v81
	v_max3_f32 v250, v250, v82, v83
	ds_read_b64_tr_b16 v[112:113], v199 offset:0x600
	ds_read_b64_tr_b16 v[114:115], v199 offset:0xe00
	v_mfma_f32_32x32x16_bf16 v[16:31], v[100:103], v[116:119], v[16:31]
	v_mov_b32_e32 v251, v250
	s_nop 1
	v_permlane32_swap_b32_e32 v250, v251
	v_max_f32_e32 v251, v251, v251
	ds_read_b64_tr_b16 v[116:117], v199 offset:0x1600
	ds_read_b64_tr_b16 v[118:119], v199 offset:0x1e00
	v_mfma_f32_32x32x16_bf16 v[16:31], v[104:107], v[120:123], v[16:31]
	v_max_f32_e32 v250, v250, v250
	v_max_f32_e32 v250, v250, v251
	ds_read_b64_tr_b16 v[120:121], v199 offset:0x2600
	ds_read_b64_tr_b16 v[122:123], v199 offset:0x2e00
	v_mfma_f32_32x32x16_bf16 v[16:31], v[108:111], v[124:127], v[16:31]
	v_sub_f32_e32 v251, v250, v208
	v_mul_f32_e32 v251, 0x3d93cd3a, v251
	ds_read_b64_tr_b16 v[124:125], v199 offset:0x3600
	ds_read_b64_tr_b16 v[126:127], v199 offset:0x3e00
	s_waitcnt lgkmcnt(0)
	v_mfma_f32_32x32x16_bf16 v[0:15], v[64:67], v[112:115], v[0:15]
	v_cmp_ge_f32_e32 vcc, s97, v251
	v_max_f32_e32 v251, v208, v208
	v_mfma_f32_32x32x16_bf16 v[0:15], v[100:103], v[116:119], v[0:15]
	v_max_f32_e32 v250, v251, v250
	v_sub_f32_e32 v251, v208, v250
	v_mfma_f32_32x32x16_bf16 v[0:15], v[104:107], v[120:123], v[0:15]
	v_mul_f32_e32 v251, 0x3dd53b94, v251
	v_exp_f32_e32 v251, v251
	v_mfma_f32_32x32x16_bf16 v[0:15], v[108:111], v[124:127], v[0:15]
	s_cmp_eq_u64 vcc, exec
	s_cselect_b64 s[42:43], -1, 0
	v_mov_b32_e32 v64, v250
	v_mov_b32_e32 v65, v251

; __device__ __forceinline__ void partialSM(f32x16& p0, f32x16& p1, float& m_reg, float& mn, float& alpha) {
;     float pmax = p0[0];
; #pragma unroll
;     for (int r = 1; r < 16; ++r) pmax = fmaxf(pmax, p0[r]);
; #pragma unroll
;     for (int r = 0; r < 16; ++r) pmax = fmaxf(pmax, p1[r]);
;     { auto rr = __builtin_amdgcn_permlane32_swap(__float_as_uint(pmax), __float_as_uint(pmax), false, false);
;       pmax = fmaxf(__uint_as_float(rr[0]), __uint_as_float(rr[1])); }
;     constexpr float C2 = 1.4426950408889634f * SCALE;
;     if (__builtin_expect(__all((pmax - m_reg) * SCALE <= THR), 1)) { mn = m_reg; alpha = 1.f; }
; template <int VB>
; __device__ __forceinline__ void pv_tile(f32x16* o, int vb0, bf16x8 pa0, bf16x8 pa1, bf16x8 pa2, bf16x8 pa3) {
;     ...
;     PV_D0(0); PV_D0(1); PV_D0(2); PV_D0(3);
.LBB0_1489:
	s_add_i32 s0, s31, 0xbf
	s_cmp_le_i32 s0, s30
	s_cbranch_scc0 .La_diag2
	ds_read_b64_tr_b16 v[214:215], v199 offset:0x4000
	ds_read_b64_tr_b16 v[216:217], v199 offset:0x4800
	ds_read_b64_tr_b16 v[218:219], v199 offset:0x5000
	ds_read_b64_tr_b16 v[220:221], v199 offset:0x5800
	ds_read_b64_tr_b16 v[232:233], v199 offset:0x6000
	ds_read_b64_tr_b16 v[234:235], v199 offset:0x6800
	ds_read_b64_tr_b16 v[242:243], v199 offset:0x7000
	ds_read_b64_tr_b16 v[244:245], v199 offset:0x7800
	s_waitcnt lgkmcnt(0)
	s_nop 0
	v_mfma_f32_32x32x16_bf16 v[48:63], v[166:169], v[214:217], v[48:63]
	v_max_f32_e32 v250, v113, v113
	v_max_f32_e32 v251, v112, v112
	ds_read_b64_tr_b16 v[214:215], v199 offset:0x4200
	ds_read_b64_tr_b16 v[216:217], v199 offset:0x4a00
	v_mfma_f32_32x32x16_bf16 v[48:63], v[170:173], v[218:221], v[48:63]
	v_max_f32_e32 v250, v251, v250
	v_max3_f32 v250, v250, v114, v115
	ds_read_b64_tr_b16 v[218:219], v199 offset:0x5200
	ds_read_b64_tr_b16 v[220:221], v199 offset:0x5a00
	v_mfma_f32_32x32x16_bf16 v[48:63], v[174:177], v[232:235], v[48:63]
	v_max3_f32 v250, v250, v116, v117
	v_max3_f32 v250, v250, v118, v119
	ds_read_b64_tr_b16 v[232:233], v199 offset:0x6200
	ds_read_b64_tr_b16 v[234:235], v199 offset:0x6a00
	v_mfma_f32_32x32x16_bf16 v[48:63], v[178:181], v[242:245], v[48:63]
	v_max3_f32 v250, v250, v120, v121
	v_max3_f32 v250, v250, v122, v123
	ds_read_b64_tr_b16 v[242:243], v199 offset:0x7200
	ds_read_b64_tr_b16 v[244:245], v199 offset:0x7a00
	s_waitcnt lgkmcnt(0)
	v_mfma_f32_32x32x16_bf16 v[32:47], v[166:169], v[214:217], v[32:47]
	v_max3_f32 v250, v250, v124, v125
	v_max3_f32 v250, v250, v126, v127
	ds_read_b64_tr_b16 v[214:215], v199 offset:0x4400
	ds_read_b64_tr_b16 v[216:217], v199 offset:0x4c00
	v_mfma_f32_32x32x16_bf16 v[32:47], v[170:173], v[218:221], v[32:47]
	v_max3_f32 v250, v250, v96, v97
	v_max3_f32 v250, v250, v98, v99
	ds_read_b64_tr_b16 v[218:219], v199 offset:0x5400
	ds_read_b64_tr_b16 v[220:221], v199 offset:0x5c00
	v_mfma_f32_32x32x16_bf16 v[32:47], v[174:177], v[232:235], v[32:47]
	v_max3_f32 v250, v250, v100, v101
	v_max3_f32 v250, v250, v102, v103
	ds_read_b64_tr_b16 v[232:233], v199 offset:0x6400
	ds_read_b64_tr_b16 v[234:235], v199 offset:0x6c00
	v_mfma_f32_32x32x16_bf16 v[32:47], v[178:181], v[242:245], v[32:47]
	v_max3_f32 v250, v250, v104, v105
	v_max3_f32 v250, v250, v106, v107
	ds_read_b64_tr_b16 v[242:243], v199 offset:0x7400
	ds_read_b64_tr_b16 v[244:245], v199 offset:0x7c00
	s_waitcnt lgkmcnt(0)
	v_mfma_f32_32x32x16_bf16 v[16:31], v[166:169], v[214:217], v[16:31]
	v_max3_f32 v250, v250, v108, v109
	v_max3_f32 v250, v250, v110, v111
	ds_read_b64_tr_b16 v[214:215], v199 offset:0x4600
	ds_read_b64_tr_b16 v[216:217], v199 offset:0x4e00
	v_mfma_f32_32x32x16_bf16 v[16:31], v[170:173], v[218:221], v[16:31]
	v_mov_b32_e32 v251, v250
	s_nop 1
	v_permlane32_swap_b32_e32 v250, v251
	v_max_f32_e32 v251, v251, v251
	ds_read_b64_tr_b16 v[218:219], v199 offset:0x5600
	ds_read_b64_tr_b16 v[220:221], v199 offset:0x5e00
	v_mfma_f32_32x32x16_bf16 v[16:31], v[174:177], v[232:235], v[16:31]
	v_max_f32_e32 v250, v250, v250
	v_max_f32_e32 v250, v250, v251
	ds_read_b64_tr_b16 v[232:233], v199 offset:0x6600
	ds_read_b64_tr_b16 v[234:235], v199 offset:0x6e00
	v_mfma_f32_32x32x16_bf16 v[16:31], v[178:181], v[242:245], v[16:31]
	v_sub_f32_e32 v251, v250, v208
	v_mul_f32_e32 v251, 0x3d93cd3a, v251
	ds_read_b64_tr_b16 v[242:243], v199 offset:0x7600
	ds_read_b64_tr_b16 v[244:245], v199 offset:0x7e00
	s_waitcnt lgkmcnt(0)
	v_mfma_f32_32x32x16_bf16 v[0:15], v[166:169], v[214:217], v[0:15]
	v_cmp_ge_f32_e32 vcc, s97, v251
	s_cmp_eq_u64 vcc, exec
	v_mfma_f32_32x32x16_bf16 v[0:15], v[170:173], v[218:221], v[0:15]
	s_cselect_b64 s[42:43], -1, 0
	v_mfma_f32_32x32x16_bf16 v[0:15], v[174:177], v[232:235], v[0:15]
	v_mfma_f32_32x32x16_bf16 v[0:15], v[178:181], v[242:245], v[0:15]
	v_mov_b32_e32 v166, v250
	v_mov_b32_e32 v167, v251

; __device__ __forceinline__ void mask_tile(f32x16& p0, f32x16& p1, int dq) {
;     const float NEG = -__builtin_inff();
; #pragma unroll
;     for (int r = 0; r < 16; ++r) {
;         const int c = (r & 3) + 8 * (r >> 2);
;         if (dq - c < 0) p0[r] = NEG;
;         if (dq - c - 32 < 0) p1[r] = NEG;
;     }
; }
; template <int VB>
; __device__ __forceinline__ void pv_tile(f32x16* o, int vb0, bf16x8 pa0, bf16x8 pa1, bf16x8 pa2, bf16x8 pa3) {
;     ...
;     PV_D0(0); PV_D0(1); PV_D0(2); PV_D0(3);
.La_diag1:
	ds_read_b64_tr_b16 v[112:113], v199 offset:0
	ds_read_b64_tr_b16 v[114:115], v199 offset:0x800
	ds_read_b64_tr_b16 v[116:117], v199 offset:0x1000
	ds_read_b64_tr_b16 v[118:119], v199 offset:0x1800
	ds_read_b64_tr_b16 v[120:121], v199 offset:0x2000
	ds_read_b64_tr_b16 v[122:123], v199 offset:0x2800
	ds_read_b64_tr_b16 v[124:125], v199 offset:0x3000
	ds_read_b64_tr_b16 v[126:127], v199 offset:0x3800
	s_waitcnt lgkmcnt(0)
	s_nop 0
	v_mfma_f32_32x32x16_bf16 v[48:63], v[64:67], v[112:115], v[48:63]
	ds_read_b64_tr_b16 v[112:113], v199 offset:0x200
	ds_read_b64_tr_b16 v[114:115], v199 offset:0xa00
	v_mfma_f32_32x32x16_bf16 v[48:63], v[100:103], v[116:119], v[48:63]
	ds_read_b64_tr_b16 v[116:117], v199 offset:0x1200
	ds_read_b64_tr_b16 v[118:119], v199 offset:0x1a00
	v_mfma_f32_32x32x16_bf16 v[48:63], v[104:107], v[120:123], v[48:63]
	ds_read_b64_tr_b16 v[120:121], v199 offset:0x2200
	ds_read_b64_tr_b16 v[122:123], v199 offset:0x2a00
	v_mfma_f32_32x32x16_bf16 v[48:63], v[108:111], v[124:127], v[48:63]
	ds_read_b64_tr_b16 v[124:125], v199 offset:0x3200
	ds_read_b64_tr_b16 v[126:127], v199 offset:0x3a00
	s_waitcnt lgkmcnt(0)
	v_mfma_f32_32x32x16_bf16 v[32:47], v[64:67], v[112:115], v[32:47]
	ds_read_b64_tr_b16 v[112:113], v199 offset:0x400
	ds_read_b64_tr_b16 v[114:115], v199 offset:0xc00
	v_mfma_f32_32x32x16_bf16 v[32:47], v[100:103], v[116:119], v[32:47]
	ds_read_b64_tr_b16 v[116:117], v199 offset:0x1400
	ds_read_b64_tr_b16 v[118:119], v199 offset:0x1c00
	v_mfma_f32_32x32x16_bf16 v[32:47], v[104:107], v[120:123], v[32:47]
	ds_read_b64_tr_b16 v[120:121], v199 offset:0x2400
	ds_read_b64_tr_b16 v[122:123], v199 offset:0x2c00
	v_mfma_f32_32x32x16_bf16 v[32:47], v[108:111], v[124:127], v[32:47]
	ds_read_b64_tr_b16 v[124:125], v199 offset:0x3400
	ds_read_b64_tr_b16 v[126:127], v199 offset:0x3c00
	s_waitcnt lgkmcnt(0)
	v_mfma_f32_32x32x16_bf16 v[16:31], v[64:67], v[112:115], v[16:31]
	ds_read_b64_tr_b16 v[112:113], v199 offset:0x600
	ds_read_b64_tr_b16 v[114:115], v199 offset:0xe00
	v_mfma_f32_32x32x16_bf16 v[16:31], v[100:103], v[116:119], v[16:31]
	ds_read_b64_tr_b16 v[116:117], v199 offset:0x1600
	ds_read_b64_tr_b16 v[118:119], v199 offset:0x1e00
	v_mfma_f32_32x32x16_bf16 v[16:31], v[104:107], v[120:123], v[16:31]
	ds_read_b64_tr_b16 v[120:121], v199 offset:0x2600
	ds_read_b64_tr_b16 v[122:123], v199 offset:0x2e00
	v_mfma_f32_32x32x16_bf16 v[16:31], v[108:111], v[124:127], v[16:31]
	ds_read_b64_tr_b16 v[124:125], v199 offset:0x3600
	ds_read_b64_tr_b16 v[126:127], v199 offset:0x3e00
	s_waitcnt lgkmcnt(0)
	v_mfma_f32_32x32x16_bf16 v[0:15], v[64:67], v[112:115], v[0:15]
	s_add_i32 s0, s31, 0x7f
	s_cmp_le_i32 s0, s30
	v_mfma_f32_32x32x16_bf16 v[0:15], v[100:103], v[116:119], v[0:15]
	v_mfma_f32_32x32x16_bf16 v[0:15], v[104:107], v[120:123], v[0:15]
	v_mfma_f32_32x32x16_bf16 v[0:15], v[108:111], v[124:127], v[0:15]
	s_cbranch_scc1 .LBB0_1483
	v_add_u32_e32 v64, 64, v209
	v_cmp_gt_i32_e64 s[96:97], 26, v64
	v_cmp_gt_i32_e32 vcc, 27, v64
	v_cmp_gt_i32_e64 s[94:95], 25, v64
	v_cmp_gt_i32_e64 s[92:93], 24, v64
	v_cndmask_b32_e32 v99, v99, v228, vcc
	s_and_b64 vcc, vcc, s[96:97]
	v_cndmask_b32_e32 v98, v98, v228, vcc
	s_and_b64 vcc, vcc, s[94:95]
	v_cmp_gt_i32_e64 s[90:91], 19, v64
	v_cndmask_b32_e32 v97, v97, v228, vcc
	s_and_b64 vcc, vcc, s[92:93]
	v_cmp_gt_i32_e64 s[88:89], 18, v64
	v_cndmask_b32_e32 v96, v96, v228, vcc
	s_and_b64 vcc, vcc, s[90:91]
	v_cmp_gt_i32_e64 s[86:87], 17, v64
	v_cndmask_b32_e32 v95, v95, v228, vcc
	s_and_b64 vcc, vcc, s[88:89]
	v_cmp_gt_i32_e64 s[84:85], 16, v64
	v_cndmask_b32_e32 v94, v94, v228, vcc
	s_and_b64 vcc, vcc, s[86:87]
	v_cmp_gt_i32_e64 s[82:83], 11, v64
	v_cndmask_b32_e32 v93, v93, v228, vcc
	s_and_b64 vcc, vcc, s[84:85]
	v_cmp_gt_i32_e64 s[80:81], 10, v64
	v_cndmask_b32_e32 v92, v92, v228, vcc
	s_and_b64 vcc, vcc, s[82:83]
	v_cmp_gt_i32_e64 s[78:79], 9, v64
	v_cndmask_b32_e32 v91, v91, v228, vcc
	s_and_b64 vcc, vcc, s[80:81]
	v_cmp_gt_i32_e64 s[76:77], 8, v64
	v_cndmask_b32_e32 v90, v90, v228, vcc
	s_and_b64 vcc, vcc, s[78:79]
	v_cmp_gt_i32_e64 s[74:75], 3, v64
	v_cndmask_b32_e32 v89, v89, v228, vcc
	s_and_b64 vcc, vcc, s[76:77]
	v_cmp_gt_i32_e64 s[72:73], 2, v64
	v_cndmask_b32_e32 v88, v88, v228, vcc
	s_and_b64 vcc, vcc, s[74:75]
	v_cmp_gt_i32_e64 s[70:71], 1, v64
	v_cndmask_b32_e32 v87, v87, v228, vcc
	s_and_b64 vcc, vcc, s[72:73]
	v_cmp_gt_i32_e64 s[4:5], 0, v64
	v_cndmask_b32_e32 v86, v86, v228, vcc
	s_and_b64 vcc, vcc, s[70:71]
	v_cndmask_b32_e32 v85, v85, v228, vcc
	s_and_b64 vcc, vcc, s[4:5]
	v_cmp_gt_i32_e64 s[68:69], 58, v64
	v_cndmask_b32_e32 v84, v84, v228, vcc
	v_cmp_gt_i32_e32 vcc, 59, v64
	v_cmp_gt_i32_e64 s[66:67], 57, v64
	v_cmp_gt_i32_e64 s[64:65], 56, v64
	v_cndmask_b32_e32 v83, v83, v228, vcc
	s_and_b64 vcc, vcc, s[68:69]
	v_cndmask_b32_e32 v82, v82, v228, vcc
	s_and_b64 vcc, vcc, s[66:67]
	v_cmp_gt_i32_e64 s[62:63], 51, v64
	v_cndmask_b32_e32 v81, v81, v228, vcc
	s_and_b64 vcc, vcc, s[64:65]
	v_cmp_gt_i32_e64 s[60:61], 50, v64
	v_cndmask_b32_e32 v80, v80, v228, vcc
	s_and_b64 vcc, vcc, s[62:63]
	v_cmp_gt_i32_e64 s[58:59], 49, v64
	v_cndmask_b32_e32 v79, v79, v228, vcc
	s_and_b64 vcc, vcc, s[60:61]
	v_cmp_gt_i32_e64 s[56:57], 48, v64
	v_cndmask_b32_e32 v78, v78, v228, vcc
	s_and_b64 vcc, vcc, s[58:59]
	v_cmp_gt_i32_e64 s[54:55], 43, v64
	v_cndmask_b32_e32 v77, v77, v228, vcc
	s_and_b64 vcc, vcc, s[56:57]
	v_cmp_gt_i32_e64 s[52:53], 42, v64
	v_cndmask_b32_e32 v76, v76, v228, vcc
	s_and_b64 vcc, vcc, s[54:55]
	v_cmp_gt_i32_e64 s[50:51], 41, v64
	v_cndmask_b32_e32 v75, v75, v228, vcc
	s_and_b64 vcc, vcc, s[52:53]
	v_cmp_gt_i32_e64 s[46:47], 40, v64
	v_cndmask_b32_e32 v74, v74, v228, vcc
	s_and_b64 vcc, vcc, s[50:51]
	v_cmp_gt_i32_e64 s[44:45], 35, v64
	v_cndmask_b32_e32 v73, v73, v228, vcc
	s_and_b64 vcc, vcc, s[46:47]
	v_cmp_gt_i32_e64 s[42:43], 34, v64
	v_cndmask_b32_e32 v72, v72, v228, vcc
	s_and_b64 vcc, vcc, s[44:45]
	v_cmp_gt_i32_e64 s[0:1], 33, v64
	v_cndmask_b32_e32 v71, v71, v228, vcc
	s_and_b64 vcc, vcc, s[42:43]
	v_cmp_gt_i32_e64 s[6:7], 32, v64
	v_cndmask_b32_e32 v70, v70, v228, vcc
	s_and_b64 vcc, vcc, s[0:1]
	v_cndmask_b32_e32 v69, v69, v228, vcc
	s_and_b64 vcc, vcc, s[6:7]
	s_mov_b32 s97, 0x41000000
	v_cndmask_b32_e32 v68, v68, v228, vcc
; __device__ __forceinline__ void partialSM(f32x16& p0, f32x16& p1, float& m_reg, float& mn, float& alpha) {
;     float pmax = p0[0];
; #pragma unroll
;     for (int r = 1; r < 16; ++r) pmax = fmaxf(pmax, p0[r]);
; #pragma unroll
;     for (int r = 0; r < 16; ++r) pmax = fmaxf(pmax, p1[r]);
;     { auto rr = __builtin_amdgcn_permlane32_swap(__float_as_uint(pmax), __float_as_uint(pmax), false, false);
;       pmax = fmaxf(__uint_as_float(rr[0]), __uint_as_float(rr[1])); }
;     constexpr float C2 = 1.4426950408889634f * SCALE;
;     if (__builtin_expect(__all((pmax - m_reg) * SCALE <= THR), 1)) { mn = m_reg; alpha = 1.f; }
;     else { mn = fmaxf(m_reg, pmax); alpha = __builtin_amdgcn_exp2f((m_reg - mn) * C2); m_reg = mn; }
.LBB0_1483:
	v_max_f32_e32 v64, v85, v85
	v_max_f32_e32 v65, v84, v84
	v_max_f32_e32 v64, v65, v64
	v_max3_f32 v64, v64, v86, v87
	v_max3_f32 v64, v64, v88, v89
	v_max3_f32 v64, v64, v90, v91
	v_max3_f32 v64, v64, v92, v93
	v_max3_f32 v64, v64, v94, v95
	v_max3_f32 v64, v64, v96, v97
	v_max3_f32 v64, v64, v98, v99
	v_max3_f32 v64, v64, v68, v69
	v_max3_f32 v64, v64, v70, v71
	v_max3_f32 v64, v64, v72, v73
	v_max3_f32 v64, v64, v74, v75
	v_max3_f32 v64, v64, v76, v77
	v_max3_f32 v64, v64, v78, v79
	v_max3_f32 v64, v64, v80, v81
	v_max3_f32 v64, v64, v82, v83
	v_mov_b32_e32 v65, v64
	s_nop 1
	v_permlane32_swap_b32_e32 v64, v65
	v_max_f32_e32 v65, v65, v65
	v_max_f32_e32 v64, v64, v64
	v_max_f32_e32 v64, v64, v65
	v_sub_f32_e32 v65, v64, v208
	v_mul_f32_e32 v65, 0x3d93cd3a, v65
	v_cmp_ge_f32_e32 vcc, s97, v65
	v_max_f32_e32 v65, v208, v208
	v_max_f32_e32 v64, v65, v64
	v_sub_f32_e32 v65, v208, v64
	v_mul_f32_e32 v65, 0x3dd53b94, v65
	v_exp_f32_e32 v65, v65
	s_cmp_eq_u64 vcc, exec
	s_cselect_b64 s[42:43], -1, 0
	s_branch .La_b1_1

; __device__ __forceinline__ void partialSM(f32x16& p0, f32x16& p1, float& m_reg, float& mn, float& alpha) {
;     float pmax = p0[0];
; #pragma unroll
;     for (int r = 1; r < 16; ++r) pmax = fmaxf(pmax, p0[r]);
; #pragma unroll
;     for (int r = 0; r < 16; ++r) pmax = fmaxf(pmax, p1[r]);
;     { auto rr = __builtin_amdgcn_permlane32_swap(__float_as_uint(pmax), __float_as_uint(pmax), false, false);
;       pmax = fmaxf(__uint_as_float(rr[0]), __uint_as_float(rr[1])); }
;     constexpr float C2 = 1.4426950408889634f * SCALE;
;     if (__builtin_expect(__all((pmax - m_reg) * SCALE <= THR), 1)) { mn = m_reg; alpha = 1.f; }
.LBB0_1491:
	v_max_f32_e32 v166, v113, v113
	v_max_f32_e32 v167, v112, v112
	v_max_f32_e32 v166, v167, v166
	v_max3_f32 v166, v166, v114, v115
	v_max3_f32 v166, v166, v116, v117
	v_max3_f32 v166, v166, v118, v119
	v_max3_f32 v166, v166, v120, v121
	v_max3_f32 v166, v166, v122, v123
	v_max3_f32 v166, v166, v124, v125
	v_max3_f32 v166, v166, v126, v127
	v_max3_f32 v166, v166, v96, v97
	v_max3_f32 v166, v166, v98, v99
	v_max3_f32 v166, v166, v100, v101
	v_max3_f32 v166, v166, v102, v103
	v_max3_f32 v166, v166, v104, v105
	v_max3_f32 v166, v166, v106, v107
	v_max3_f32 v166, v166, v108, v109
	v_max3_f32 v166, v166, v110, v111
	v_mov_b32_e32 v167, v166
	s_nop 1
	v_permlane32_swap_b32_e32 v166, v167
	v_max_f32_e32 v167, v167, v167
	v_max_f32_e32 v166, v166, v166
	v_max_f32_e32 v166, v166, v167
	v_sub_f32_e32 v167, v166, v208
	v_mul_f32_e32 v167, 0x3d93cd3a, v167
	v_cmp_ge_f32_e32 vcc, s97, v167
	s_cmp_eq_u64 vcc, exec
	s_cselect_b64 s[42:43], -1, 0
	s_branch .La_b1_2
	s_nop 0
	s_nop 0
	s_nop 0
	s_nop 0
	s_nop 0
	s_nop 0
	s_nop 0
